# GLA prep cumsum: batched LDS reads (4x16) with in-register sequential adds; conv GELU in sigmoid form x*(1-r) with folded exp constant (28 fewer VALU per step)
# speedup vs baseline: 1.0568x; 1.0099x over previous
.LBB0_159:
	s_or_b64 exec, exec, s[38:39]
	v_add_co_u32_e32 v2, vcc, 0xb581000, v162
	v_lshlrev_b32_e32 v172, 16, v116
	s_nop 0
	v_addc_co_u32_e32 v3, vcc, 0, v163, vcc
	global_load_dwordx4 v[88:91], v[2:3], off offset:1536
	v_lshlrev_b32_e32 v2, 16, v136
	v_and_b32_e32 v3, 0xffff0000, v136
	v_and_b32_e32 v173, 0xffff0000, v116
	v_pk_fma_f32 v[2:3], v[64:65], v[2:3], v[84:85]
	v_lshlrev_b32_e32 v174, 16, v96
	v_pk_fma_f32 v[236:237], v[72:73], v[172:173], v[2:3]
	v_and_b32_e32 v175, 0xffff0000, v96
	v_lshlrev_b32_e32 v238, 16, v132
	v_and_b32_e32 v239, 0xffff0000, v132
	v_pk_fma_f32 v[236:237], v[32:33], v[174:175], v[236:237]
	v_lshlrev_b32_e32 v182, 16, v120
	v_and_b32_e32 v183, 0xffff0000, v120
	v_pk_fma_f32 v[236:237], v[36:37], v[238:239], v[236:237]
	v_lshlrev_b32_e32 v188, 16, v100
	v_and_b32_e32 v189, 0xffff0000, v100
	v_pk_fma_f32 v[236:237], v[40:41], v[182:183], v[236:237]
	v_lshlrev_b32_e32 v238, 16, v112
	v_and_b32_e32 v239, 0xffff0000, v112
	v_pk_fma_f32 v[236:237], v[44:45], v[188:189], v[236:237]
	v_lshlrev_b32_e32 v190, 16, v124
	v_and_b32_e32 v191, 0xffff0000, v124
	v_pk_fma_f32 v[236:237], v[48:49], v[238:239], v[236:237]
	v_lshlrev_b32_e32 v194, 16, v92
	v_and_b32_e32 v195, 0xffff0000, v92
	v_pk_fma_f32 v[236:237], v[52:53], v[190:191], v[236:237]
	v_lshlrev_b32_e32 v238, 16, v128
	v_pk_fma_f32 v[236:237], v[56:57], v[194:195], v[236:237]
	v_and_b32_e32 v239, 0xffff0000, v128
	v_mul_f32_e32 v0, 0x3d372713, v236
	v_mul_f32_e32 v0, v236, v0
	v_fma_f32 v0, v236, v0, v236
	v_mul_f32_e32 v0, 0x40135761, v0
	v_exp_f32_e32 v242, v0
	v_mul_f32_e32 v0, 0x3d372713, v237
	v_mul_f32_e32 v0, v237, v0
	v_fma_f32 v0, v237, v0, v237
	v_mul_f32_e32 v0, 0x40135761, v0
	v_exp_f32_e32 v243, v0
	v_lshlrev_b32_e32 v2, 16, v137
	v_and_b32_e32 v3, 0xffff0000, v137
	v_lshlrev_b32_e32 v176, 16, v117
	v_pk_add_f32 v[242:243], v[242:243], 1.0 op_sel_hi:[1,0]
	v_and_b32_e32 v177, 0xffff0000, v117
	v_rcp_f32_e32 v243, v243
	v_pk_fma_f32 v[2:3], v[66:67], v[2:3], v[86:87]
	v_lshlrev_b32_e32 v178, 16, v97
	v_pk_fma_f32 v[204:205], v[74:75], v[176:177], v[2:3]
	v_fma_f32 v237, -v237, v243, v237
	v_rcp_f32_e32 v242, v242
	v_and_b32_e32 v179, 0xffff0000, v97
	v_lshlrev_b32_e32 v240, 16, v133
	v_and_b32_e32 v241, 0xffff0000, v133
	v_fma_f32 v236, -v236, v242, v236
	v_pk_fma_f32 v[204:205], v[34:35], v[178:179], v[204:205]
	v_lshlrev_b32_e32 v164, 16, v121
	v_and_b32_e32 v165, 0xffff0000, v121
	v_pk_fma_f32 v[204:205], v[38:39], v[240:241], v[204:205]
	v_lshlrev_b32_e32 v166, 16, v101
	v_and_b32_e32 v167, 0xffff0000, v101
	v_pk_mul_f32 v[236:237], v[236:237], v[238:239]
	v_pk_fma_f32 v[204:205], v[42:43], v[164:165], v[204:205]
	v_cvt_pk_bf16_f32 v112, v236, v237
	v_lshlrev_b32_e32 v236, 16, v113
	v_and_b32_e32 v237, 0xffff0000, v113
	v_pk_fma_f32 v[204:205], v[46:47], v[166:167], v[204:205]
	v_lshlrev_b32_e32 v168, 16, v125
	v_and_b32_e32 v169, 0xffff0000, v125
	v_pk_fma_f32 v[204:205], v[50:51], v[236:237], v[204:205]
	v_lshlrev_b32_e32 v170, 16, v93
	v_and_b32_e32 v171, 0xffff0000, v93
	v_pk_fma_f32 v[204:205], v[54:55], v[168:169], v[204:205]
	v_lshlrev_b32_e32 v2, 16, v138
	v_pk_fma_f32 v[204:205], v[58:59], v[170:171], v[204:205]
	v_and_b32_e32 v3, 0xffff0000, v138
	v_mul_f32_e32 v0, 0x3d372713, v204
	v_mul_f32_e32 v0, v204, v0
	v_fma_f32 v0, v204, v0, v204
	v_mul_f32_e32 v0, 0x40135761, v0
	v_exp_f32_e32 v236, v0
	v_mul_f32_e32 v0, 0x3d372713, v205
	v_mul_f32_e32 v0, v205, v0
	v_fma_f32 v0, v205, v0, v205
	v_mul_f32_e32 v0, 0x40135761, v0
	v_exp_f32_e32 v237, v0
	v_lshlrev_b32_e32 v180, 16, v118
	v_and_b32_e32 v181, 0xffff0000, v118
	v_pk_add_f32 v[236:237], v[236:237], 1.0 op_sel_hi:[1,0]
	v_pk_fma_f32 v[2:3], v[60:61], v[2:3], v[80:81]
	v_rcp_f32_e32 v237, v237
	v_lshlrev_b32_e32 v128, 16, v129
	v_and_b32_e32 v129, 0xffff0000, v129
	v_pk_fma_f32 v[200:201], v[68:69], v[180:181], v[2:3]
	v_fma_f32 v205, -v205, v237, v205
	v_rcp_f32_e32 v236, v236
	v_lshlrev_b32_e32 v184, 16, v98
	v_and_b32_e32 v185, 0xffff0000, v98
	v_lshlrev_b32_e32 v202, 16, v134
	v_fma_f32 v204, -v204, v236, v204
	v_and_b32_e32 v203, 0xffff0000, v134
	v_lshlrev_b32_e32 v2, 16, v139
	v_and_b32_e32 v3, 0xffff0000, v139
	v_pk_mul_f32 v[128:129], v[204:205], v[128:129]
	v_lshlrev_b32_e32 v138, 16, v122
	v_cvt_pk_bf16_f32 v113, v128, v129
	v_pk_fma_f32 v[128:129], v[4:5], v[184:185], v[200:201]
	v_and_b32_e32 v139, 0xffff0000, v122
	v_pk_fma_f32 v[128:129], v[8:9], v[202:203], v[128:129]
	v_lshlrev_b32_e32 v146, 16, v102
	v_and_b32_e32 v147, 0xffff0000, v102
	v_pk_fma_f32 v[128:129], v[12:13], v[138:139], v[128:129]
	v_lshlrev_b32_e32 v200, 16, v114
	v_and_b32_e32 v201, 0xffff0000, v114
	v_pk_fma_f32 v[128:129], v[16:17], v[146:147], v[128:129]
	v_lshlrev_b32_e32 v148, 16, v126
	v_and_b32_e32 v149, 0xffff0000, v126
	v_pk_fma_f32 v[128:129], v[20:21], v[200:201], v[128:129]
	v_lshlrev_b32_e32 v160, 16, v94
	v_and_b32_e32 v161, 0xffff0000, v94
	v_pk_fma_f32 v[128:129], v[24:25], v[148:149], v[128:129]
	v_lshlrev_b32_e32 v200, 16, v130
	v_pk_fma_f32 v[128:129], v[28:29], v[160:161], v[128:129]
	v_and_b32_e32 v201, 0xffff0000, v130
	v_mul_f32_e32 v0, 0x3d372713, v128
	v_mul_f32_e32 v0, v128, v0
	v_fma_f32 v0, v128, v0, v128
	v_mul_f32_e32 v0, 0x40135761, v0
	v_exp_f32_e32 v202, v0
	v_mul_f32_e32 v0, 0x3d372713, v129
	v_mul_f32_e32 v0, v129, v0
	v_fma_f32 v0, v129, v0, v129
	v_mul_f32_e32 v0, 0x40135761, v0
	v_exp_f32_e32 v203, v0
	v_lshlrev_b32_e32 v186, 16, v119
	v_and_b32_e32 v187, 0xffff0000, v119
	v_pk_add_f32 v[202:203], v[202:203], 1.0 op_sel_hi:[1,0]
	v_pk_fma_f32 v[2:3], v[62:63], v[2:3], v[82:83]
	v_rcp_f32_e32 v203, v203
	v_pk_fma_f32 v[196:197], v[70:71], v[186:187], v[2:3]
	v_lshlrev_b32_e32 v192, 16, v99
	v_and_b32_e32 v193, 0xffff0000, v99
	v_fma_f32 v129, -v129, v203, v129
	v_rcp_f32_e32 v202, v202
	v_lshlrev_b32_e32 v198, 16, v135
	v_and_b32_e32 v199, 0xffff0000, v135
	v_lshlrev_b32_e32 v2, 16, v123
	v_fma_f32 v128, -v128, v202, v128
	v_and_b32_e32 v3, 0xffff0000, v123
	v_lshlrev_b32_e32 v132, 16, v103
	v_and_b32_e32 v133, 0xffff0000, v103
	v_pk_mul_f32 v[128:129], v[128:129], v[200:201]
	v_lshlrev_b32_e32 v134, 16, v127
	v_cvt_pk_bf16_f32 v114, v128, v129
	v_pk_fma_f32 v[128:129], v[6:7], v[192:193], v[196:197]
	v_lshlrev_b32_e32 v196, 16, v115
	v_pk_fma_f32 v[128:129], v[10:11], v[198:199], v[128:129]
	v_and_b32_e32 v197, 0xffff0000, v115
	v_pk_fma_f32 v[128:129], v[14:15], v[2:3], v[128:129]
	v_and_b32_e32 v135, 0xffff0000, v127
	v_pk_fma_f32 v[128:129], v[18:19], v[132:133], v[128:129]
	v_lshlrev_b32_e32 v136, 16, v95
	v_pk_fma_f32 v[128:129], v[22:23], v[196:197], v[128:129]
	v_and_b32_e32 v137, 0xffff0000, v95
	v_pk_fma_f32 v[128:129], v[26:27], v[134:135], v[128:129]
	v_lshlrev_b32_e32 v130, 16, v131
	v_pk_fma_f32 v[128:129], v[30:31], v[136:137], v[128:129]
	v_and_b32_e32 v131, 0xffff0000, v131
	v_mul_f32_e32 v0, 0x3d372713, v128
	v_mul_f32_e32 v0, v128, v0
	v_fma_f32 v0, v128, v0, v128
	v_mul_f32_e32 v0, 0x40135761, v0
	v_exp_f32_e32 v196, v0
	v_mul_f32_e32 v0, 0x3d372713, v129
	v_mul_f32_e32 v0, v129, v0
	v_fma_f32 v0, v129, v0, v129
	v_mul_f32_e32 v0, 0x40135761, v0
	v_exp_f32_e32 v197, v0
	s_add_u32 s34, s34, 0x1600
	s_addc_u32 s35, s35, 0
	v_pk_add_f32 v[196:197], v[196:197], 1.0 op_sel_hi:[1,0]
	v_add_u32_e32 v234, 1, v234
	v_rcp_f32_e32 v197, v197
	s_cmp_eq_u32 s34, 0x2aa00
	v_fma_f32 v129, -v129, v197, v129
	v_rcp_f32_e32 v196, v196
	s_mov_b32 s38, 0xb580000
	v_fma_f32 v128, -v128, v196, v128
	s_nop 0
	v_pk_mul_f32 v[128:129], v[128:129], v[130:131]
	s_nop 0
	v_cvt_pk_bf16_f32 v115, v128, v129
	v_add_co_u32_e32 v128, vcc, s38, v162
	s_nop 1
	v_addc_co_u32_e32 v129, vcc, 0, v163, vcc
	global_store_dwordx4 v[128:129], v[112:115], off
	s_cbranch_scc1 .LBB0_131
	s_nop 0
	v_mov_b64_e32 v[112:113], v[124:125]
	v_mov_b64_e32 v[134:135], v[122:123]
	v_mov_b64_e32 v[138:139], v[118:119]
	s_waitcnt vmcnt(1)
	v_mov_b64_e32 v[130:131], v[90:91]
	v_mov_b64_e32 v[114:115], v[126:127]
	v_mov_b64_e32 v[132:133], v[120:121]
	v_mov_b64_e32 v[136:137], v[116:117]
	v_mov_b64_e32 v[128:129], v[88:89]
	s_branch .LBB0_153

.LBB0_596:
	ds_read_b32 v202, v143
	ds_read_b32 v203, v143 offset:196
	ds_read_b32 v204, v143 offset:392
	ds_read_b32 v205, v143 offset:588
	ds_read_b32 v234, v143 offset:784
	ds_read_b32 v235, v143 offset:980
	ds_read_b32 v236, v143 offset:1176
	ds_read_b32 v237, v143 offset:1372
	ds_read_b32 v238, v143 offset:1568
	ds_read_b32 v239, v143 offset:1764
	ds_read_b32 v240, v143 offset:1960
	ds_read_b32 v241, v143 offset:2156
	ds_read_b32 v242, v143 offset:2352
	ds_read_b32 v243, v143 offset:2548
	ds_read_b32 v244, v143 offset:2744
	ds_read_b32 v245, v143 offset:2940
	s_waitcnt lgkmcnt(15)
	v_add_f32_e32 v202, v2, v202
	s_waitcnt lgkmcnt(14)
	v_add_f32_e32 v203, v202, v203
	s_waitcnt lgkmcnt(13)
	v_add_f32_e32 v204, v203, v204
	s_waitcnt lgkmcnt(12)
	v_add_f32_e32 v205, v204, v205
	s_waitcnt lgkmcnt(11)
	v_add_f32_e32 v234, v205, v234
	s_waitcnt lgkmcnt(10)
	v_add_f32_e32 v235, v234, v235
	s_waitcnt lgkmcnt(9)
	v_add_f32_e32 v236, v235, v236
	s_waitcnt lgkmcnt(8)
	v_add_f32_e32 v237, v236, v237
	s_waitcnt lgkmcnt(7)
	v_add_f32_e32 v238, v237, v238
	s_waitcnt lgkmcnt(6)
	v_add_f32_e32 v239, v238, v239
	s_waitcnt lgkmcnt(5)
	v_add_f32_e32 v240, v239, v240
	s_waitcnt lgkmcnt(4)
	v_add_f32_e32 v241, v240, v241
	s_waitcnt lgkmcnt(3)
	v_add_f32_e32 v242, v241, v242
	s_waitcnt lgkmcnt(2)
	v_add_f32_e32 v243, v242, v243
	s_waitcnt lgkmcnt(1)
	v_add_f32_e32 v244, v243, v244
	s_waitcnt lgkmcnt(0)
	v_add_f32_e32 v245, v244, v245
	ds_write_b32 v143, v202
	ds_write_b32 v143, v203 offset:196
	ds_write_b32 v143, v204 offset:392
	ds_write_b32 v143, v205 offset:588
	ds_write_b32 v143, v234 offset:784
	ds_write_b32 v143, v235 offset:980
	ds_write_b32 v143, v236 offset:1176
	ds_write_b32 v143, v237 offset:1372
	ds_write_b32 v143, v238 offset:1568
	ds_write_b32 v143, v239 offset:1764
	ds_write_b32 v143, v240 offset:1960
	ds_write_b32 v143, v241 offset:2156
	ds_write_b32 v143, v242 offset:2352
	ds_write_b32 v143, v243 offset:2548
	ds_write_b32 v143, v244 offset:2744
	ds_write_b32 v143, v245 offset:2940
	v_mov_b32_e32 v2, v245
	ds_read_b32 v202, v143 offset:3136
	ds_read_b32 v203, v143 offset:3332
	ds_read_b32 v204, v143 offset:3528
	ds_read_b32 v205, v143 offset:3724
	ds_read_b32 v234, v143 offset:3920
	ds_read_b32 v235, v143 offset:4116
	ds_read_b32 v236, v143 offset:4312
	ds_read_b32 v237, v143 offset:4508
	ds_read_b32 v238, v143 offset:4704
	ds_read_b32 v239, v143 offset:4900
	ds_read_b32 v240, v143 offset:5096
	ds_read_b32 v241, v143 offset:5292
	ds_read_b32 v242, v143 offset:5488
	ds_read_b32 v243, v143 offset:5684
	ds_read_b32 v244, v143 offset:5880
	ds_read_b32 v245, v143 offset:6076
	s_waitcnt lgkmcnt(15)
	v_add_f32_e32 v202, v2, v202
	s_waitcnt lgkmcnt(14)
	v_add_f32_e32 v203, v202, v203
	s_waitcnt lgkmcnt(13)
	v_add_f32_e32 v204, v203, v204
	s_waitcnt lgkmcnt(12)
	v_add_f32_e32 v205, v204, v205
	s_waitcnt lgkmcnt(11)
	v_add_f32_e32 v234, v205, v234
	s_waitcnt lgkmcnt(10)
	v_add_f32_e32 v235, v234, v235
	s_waitcnt lgkmcnt(9)
	v_add_f32_e32 v236, v235, v236
	s_waitcnt lgkmcnt(8)
	v_add_f32_e32 v237, v236, v237
	s_waitcnt lgkmcnt(7)
	v_add_f32_e32 v238, v237, v238
	s_waitcnt lgkmcnt(6)
	v_add_f32_e32 v239, v238, v239
	s_waitcnt lgkmcnt(5)
	v_add_f32_e32 v240, v239, v240
	s_waitcnt lgkmcnt(4)
	v_add_f32_e32 v241, v240, v241
	s_waitcnt lgkmcnt(3)
	v_add_f32_e32 v242, v241, v242
	s_waitcnt lgkmcnt(2)
	v_add_f32_e32 v243, v242, v243
	s_waitcnt lgkmcnt(1)
	v_add_f32_e32 v244, v243, v244
	s_waitcnt lgkmcnt(0)
	v_add_f32_e32 v245, v244, v245
	ds_write_b32 v143, v202 offset:3136
	ds_write_b32 v143, v203 offset:3332
	ds_write_b32 v143, v204 offset:3528
	ds_write_b32 v143, v205 offset:3724
	ds_write_b32 v143, v234 offset:3920
	ds_write_b32 v143, v235 offset:4116
	ds_write_b32 v143, v236 offset:4312
	ds_write_b32 v143, v237 offset:4508
	ds_write_b32 v143, v238 offset:4704
	ds_write_b32 v143, v239 offset:4900
	ds_write_b32 v143, v240 offset:5096
	ds_write_b32 v143, v241 offset:5292
	ds_write_b32 v143, v242 offset:5488
	ds_write_b32 v143, v243 offset:5684
	ds_write_b32 v143, v244 offset:5880
	ds_write_b32 v143, v245 offset:6076
	v_mov_b32_e32 v2, v245
	ds_read_b32 v202, v143 offset:6272
	ds_read_b32 v203, v143 offset:6468
	ds_read_b32 v204, v143 offset:6664
	ds_read_b32 v205, v143 offset:6860
	ds_read_b32 v234, v143 offset:7056
	ds_read_b32 v235, v143 offset:7252
	ds_read_b32 v236, v143 offset:7448
	ds_read_b32 v237, v143 offset:7644
	ds_read_b32 v238, v143 offset:7840
	ds_read_b32 v239, v143 offset:8036
	ds_read_b32 v240, v143 offset:8232
	ds_read_b32 v241, v143 offset:8428
	ds_read_b32 v242, v143 offset:8624
	ds_read_b32 v243, v143 offset:8820
	ds_read_b32 v244, v143 offset:9016
	ds_read_b32 v245, v143 offset:9212
	s_waitcnt lgkmcnt(15)
	v_add_f32_e32 v202, v2, v202
	s_waitcnt lgkmcnt(14)
	v_add_f32_e32 v203, v202, v203
	s_waitcnt lgkmcnt(13)
	v_add_f32_e32 v204, v203, v204
	s_waitcnt lgkmcnt(12)
	v_add_f32_e32 v205, v204, v205
	s_waitcnt lgkmcnt(11)
	v_add_f32_e32 v234, v205, v234
	s_waitcnt lgkmcnt(10)
	v_add_f32_e32 v235, v234, v235
	s_waitcnt lgkmcnt(9)
	v_add_f32_e32 v236, v235, v236
	s_waitcnt lgkmcnt(8)
	v_add_f32_e32 v237, v236, v237
	s_waitcnt lgkmcnt(7)
	v_add_f32_e32 v238, v237, v238
	s_waitcnt lgkmcnt(6)
	v_add_f32_e32 v239, v238, v239
	s_waitcnt lgkmcnt(5)
	v_add_f32_e32 v240, v239, v240
	s_waitcnt lgkmcnt(4)
	v_add_f32_e32 v241, v240, v241
	s_waitcnt lgkmcnt(3)
	v_add_f32_e32 v242, v241, v242
	s_waitcnt lgkmcnt(2)
	v_add_f32_e32 v243, v242, v243
	s_waitcnt lgkmcnt(1)
	v_add_f32_e32 v244, v243, v244
	s_waitcnt lgkmcnt(0)
	v_add_f32_e32 v245, v244, v245
	ds_write_b32 v143, v202 offset:6272
	ds_write_b32 v143, v203 offset:6468
	ds_write_b32 v143, v204 offset:6664
	ds_write_b32 v143, v205 offset:6860
	ds_write_b32 v143, v234 offset:7056
	ds_write_b32 v143, v235 offset:7252
	ds_write_b32 v143, v236 offset:7448
	ds_write_b32 v143, v237 offset:7644
	ds_write_b32 v143, v238 offset:7840
	ds_write_b32 v143, v239 offset:8036
	ds_write_b32 v143, v240 offset:8232
	ds_write_b32 v143, v241 offset:8428
	ds_write_b32 v143, v242 offset:8624
	ds_write_b32 v143, v243 offset:8820
	ds_write_b32 v143, v244 offset:9016
	ds_write_b32 v143, v245 offset:9212
	v_mov_b32_e32 v2, v245
	ds_read_b32 v202, v143 offset:9408
	ds_read_b32 v203, v143 offset:9604
	ds_read_b32 v204, v143 offset:9800
	ds_read_b32 v205, v143 offset:9996
	ds_read_b32 v234, v143 offset:10192
	ds_read_b32 v235, v143 offset:10388
	ds_read_b32 v236, v143 offset:10584
	ds_read_b32 v237, v143 offset:10780
	ds_read_b32 v238, v143 offset:10976
	ds_read_b32 v239, v143 offset:11172
	ds_read_b32 v240, v143 offset:11368
	ds_read_b32 v241, v143 offset:11564
	ds_read_b32 v242, v143 offset:11760
	ds_read_b32 v243, v143 offset:11956
	ds_read_b32 v244, v143 offset:12152
	ds_read_b32 v245, v143 offset:12348
	s_waitcnt lgkmcnt(15)
	v_add_f32_e32 v202, v2, v202
	s_waitcnt lgkmcnt(14)
	v_add_f32_e32 v203, v202, v203
	s_waitcnt lgkmcnt(13)
	v_add_f32_e32 v204, v203, v204
	s_waitcnt lgkmcnt(12)
	v_add_f32_e32 v205, v204, v205
	s_waitcnt lgkmcnt(11)
	v_add_f32_e32 v234, v205, v234
	s_waitcnt lgkmcnt(10)
	v_add_f32_e32 v235, v234, v235
	s_waitcnt lgkmcnt(9)
	v_add_f32_e32 v236, v235, v236
	s_waitcnt lgkmcnt(8)
	v_add_f32_e32 v237, v236, v237
	s_waitcnt lgkmcnt(7)
	v_add_f32_e32 v238, v237, v238
	s_waitcnt lgkmcnt(6)
	v_add_f32_e32 v239, v238, v239
	s_waitcnt lgkmcnt(5)
	v_add_f32_e32 v240, v239, v240
	s_waitcnt lgkmcnt(4)
	v_add_f32_e32 v241, v240, v241
	s_waitcnt lgkmcnt(3)
	v_add_f32_e32 v242, v241, v242
	s_waitcnt lgkmcnt(2)
	v_add_f32_e32 v243, v242, v243
	s_waitcnt lgkmcnt(1)
	v_add_f32_e32 v244, v243, v244
	s_waitcnt lgkmcnt(0)
	v_add_f32_e32 v245, v244, v245
	ds_write_b32 v143, v202 offset:9408
	ds_write_b32 v143, v203 offset:9604
	ds_write_b32 v143, v204 offset:9800
	ds_write_b32 v143, v205 offset:9996
	ds_write_b32 v143, v234 offset:10192
	ds_write_b32 v143, v235 offset:10388
	ds_write_b32 v143, v236 offset:10584
	ds_write_b32 v143, v237 offset:10780
	ds_write_b32 v143, v238 offset:10976
	ds_write_b32 v143, v239 offset:11172
	ds_write_b32 v143, v240 offset:11368
	ds_write_b32 v143, v241 offset:11564
	ds_write_b32 v143, v242 offset:11760
	ds_write_b32 v143, v243 offset:11956
	ds_write_b32 v143, v244 offset:12152
	ds_write_b32 v143, v245 offset:12348
	v_mov_b32_e32 v2, v245
	v_or_b32_e32 v68, s73, v105
	v_ashrrev_i32_e32 v69, 31, v68
	v_lshlrev_b64 v[68:69], 2, v[68:69]
	v_or_b32_e32 v3, v68, v112
	v_mad_u64_u32 v[70:71], s[38:39], v3, s90, v[98:99]
	v_mad_i32_i24 v71, v69, s90, v71
	global_store_dword v[70:71], v2, off
